# bias-add in the softmax phases: packed v_pk_add_f32 replaced by scalar v_add_f32 pairs (bit-identical)
# speedup vs baseline: 1.0068x; 1.0066x over previous
; #define LAS3 __attribute__((address_space(3)))
; template <int MODE>
; __device__ __forceinline__ void attn_unit(const Tensors& T0, int ureq, int b, int hh, int qblk, LAS3 char* shm, const bool dummy = false) {
;     ...
;     if (near) {
;       const LAS3 float* tp = tab + (MODE ? 0 : sub * TABW) + (k0 - q0w - r32 + 4 * hi + TAB0);
; #pragma unroll
;       for (int r = 0; r < 16; ++r) { C0[r] += tp[(r & 3) + 8 * (r >> 2)]; C1[r] += tp[(r & 3) + 8 * (r >> 2) + 32]; }
;     }
.LBB0_99:
	v_or_b32_e32 v115, s18, v186
	v_lshl_add_u32 v114, v176, 2, s57
	v_lshlrev_b32_e32 v115, 2, v115
	v_sub_u32_e32 v177, v114, v115
	v_add_u32_e32 v114, 0x480, v177
	v_add_u32_e32 v116, 0x500, v177
	v_add_u32_e32 v118, 0x488, v177
	v_add_u32_e32 v120, 0x508, v177
	v_add_u32_e32 v122, 0x4a0, v177
	v_add_u32_e32 v124, 0x520, v177
	v_add_u32_e32 v160, 0x4a8, v177
	v_add_u32_e32 v162, 0x528, v177
	v_add_u32_e32 v164, 0x4c0, v177
	v_add_u32_e32 v166, 0x540, v177
	v_add_u32_e32 v168, 0x4c8, v177
	v_add_u32_e32 v170, 0x548, v177
	v_add_u32_e32 v200, 0x560, v177
	v_add_u32_e32 v178, 0x4e8, v177
	ds_read2_b32 v[114:115], v114 offset1:1
	ds_read2_b32 v[116:117], v116 offset1:1
	ds_read2_b32 v[118:119], v118 offset1:1
	ds_read2_b32 v[120:121], v120 offset1:1
	ds_read2_b32 v[122:123], v122 offset1:1
	ds_read2_b32 v[124:125], v124 offset1:1
	ds_read2_b32 v[160:161], v160 offset1:1
	ds_read2_b32 v[162:163], v162 offset1:1
	ds_read2_b32 v[164:165], v164 offset1:1
	ds_read2_b32 v[166:167], v166 offset1:1
	ds_read2_b32 v[168:169], v168 offset1:1
	ds_read2_b32 v[170:171], v170 offset1:1
	v_add_u32_e32 v189, 0x4e0, v177
	ds_read2_b32 v[178:179], v178 offset1:1
	ds_read2_b32 v[198:199], v189 offset1:1
	v_add_u32_e32 v177, 0x568, v177
	ds_read2_b32 v[200:201], v200 offset1:1
	ds_read2_b32 v[202:203], v177 offset1:1
	s_waitcnt lgkmcnt(5)
	v_add_f32_e32 v106, v106, v168
	v_add_f32_e32 v107, v107, v169
	s_waitcnt lgkmcnt(3)
	v_add_f32_e32 v110, v110, v178
	v_add_f32_e32 v111, v111, v179
	s_waitcnt lgkmcnt(2)
	v_add_f32_e32 v108, v108, v198
	v_add_f32_e32 v109, v109, v199
	v_add_f32_e32 v104, v104, v164
	v_add_f32_e32 v105, v105, v165
	v_add_f32_e32 v102, v102, v160
	v_add_f32_e32 v103, v103, v161
	v_add_f32_e32 v100, v100, v122
	v_add_f32_e32 v101, v101, v123
	v_add_f32_e32 v98, v98, v118
	v_add_f32_e32 v99, v99, v119
	v_add_f32_e32 v96, v96, v114
	v_add_f32_e32 v97, v97, v115
	s_waitcnt lgkmcnt(0)
	v_add_f32_e32 v94, v94, v202
	v_add_f32_e32 v95, v95, v203
	v_add_f32_e32 v92, v92, v200
	v_add_f32_e32 v93, v93, v201
	v_add_f32_e32 v90, v90, v170
	v_add_f32_e32 v91, v91, v171
	v_add_f32_e32 v88, v88, v166
	v_add_f32_e32 v89, v89, v167
	v_add_f32_e32 v86, v86, v162
	v_add_f32_e32 v87, v87, v163
	v_add_f32_e32 v84, v84, v124
	v_add_f32_e32 v85, v85, v125
	v_add_f32_e32 v82, v82, v120
	v_add_f32_e32 v83, v83, v121
	v_add_f32_e32 v80, v80, v116
	v_add_f32_e32 v81, v81, v117

; #define LAS3 __attribute__((address_space(3)))
; template <int MODE>
; __device__ __forceinline__ void attn_unit(const Tensors& T0, int ureq, int b, int hh, int qblk, LAS3 char* shm, const bool dummy = false) {
;     ...
;     if (near) {
;       const LAS3 float* tp = tab + (MODE ? 0 : sub * TABW) + (k0 - q0w - r32 + 4 * hi + TAB0);
; #pragma unroll
;       for (int r = 0; r < 16; ++r) { C0[r] += tp[(r & 3) + 8 * (r >> 2)]; C1[r] += tp[(r & 3) + 8 * (r >> 2) + 32]; }
;     }
.Lm1_nodma_g0:
	s_cmpk_gt_u32 s95, 0x172
	s_cbranch_scc1 .LBB0_121
	ds_read2_b32 v[160:161], v203 offset1:1
	ds_read2_b32 v[162:163], v203 offset0:2 offset1:3
	ds_read2_b32 v[164:165], v203 offset0:8 offset1:9
	ds_read2_b32 v[166:167], v203 offset0:10 offset1:11
	ds_read2_b32 v[168:169], v203 offset0:16 offset1:17
	ds_read2_b32 v[170:171], v203 offset0:18 offset1:19
	ds_read2_b32 v[206:207], v203 offset0:24 offset1:25
	ds_read2_b32 v[208:209], v203 offset0:26 offset1:27
	ds_read2_b32 v[210:211], v203 offset0:32 offset1:33
	ds_read2_b32 v[212:213], v203 offset0:34 offset1:35
	ds_read2_b32 v[214:215], v203 offset0:40 offset1:41
	ds_read2_b32 v[216:217], v203 offset0:42 offset1:43
	s_waitcnt lgkmcnt(11)
	v_add_f32_e32 v112, v112, v160
	v_add_f32_e32 v113, v113, v161
	s_waitcnt lgkmcnt(5)
	v_add_f32_e32 v124, v124, v206
	v_add_f32_e32 v125, v125, v207
	v_add_f32_e32 v122, v122, v170
	v_add_f32_e32 v123, v123, v171
	v_add_f32_e32 v120, v120, v168
	v_add_f32_e32 v121, v121, v169
	ds_read2_b32 v[160:161], v203 offset0:48 offset1:49
	ds_read2_b32 v[168:169], v203 offset0:50 offset1:51
	ds_read2_b32 v[170:171], v203 offset0:56 offset1:57
	ds_read2_b32 v[206:207], v203 offset0:58 offset1:59
	s_waitcnt lgkmcnt(8)
	v_add_f32_e32 v126, v126, v208
	v_add_f32_e32 v127, v127, v209
	v_add_f32_e32 v118, v118, v166
	v_add_f32_e32 v119, v119, v167
	v_add_f32_e32 v116, v116, v164
	v_add_f32_e32 v117, v117, v165
	v_add_f32_e32 v114, v114, v162
	v_add_f32_e32 v115, v115, v163
	s_waitcnt lgkmcnt(7)
	v_add_f32_e32 v96, v96, v210
	v_add_f32_e32 v97, v97, v211
	s_waitcnt lgkmcnt(0)
	v_add_f32_e32 v110, v110, v206
	v_add_f32_e32 v111, v111, v207
	v_add_f32_e32 v108, v108, v170
	v_add_f32_e32 v109, v109, v171
	v_add_f32_e32 v106, v106, v168
	v_add_f32_e32 v107, v107, v169
	v_add_f32_e32 v104, v104, v160
	v_add_f32_e32 v105, v105, v161
	v_add_f32_e32 v102, v102, v216
	v_add_f32_e32 v103, v103, v217
	v_add_f32_e32 v100, v100, v214
	v_add_f32_e32 v101, v101, v215
	v_add_f32_e32 v98, v98, v212
	v_add_f32_e32 v99, v99, v213

; #define LAS3 __attribute__((address_space(3)))
; __device__ __forceinline__ int crow(int r, int hi) { return (r & 3) + 8 * (r >> 2) + 4 * hi; }
; __device__ __forceinline__ float max2f(float a, float b) { float r; asm("v_max_f32_e32 %0, %1, %2" : "=v"(r) : "v"(a), "v"(b)); return r; }
; __device__ __forceinline__ float max3f(float a, float b, float c) { float r; asm("v_max3_f32 %0, %1, %2, %3" : "=v"(r) : "v"(a), "v"(b), "v"(c)); return r; }
; template <int MODE>
; __device__ __forceinline__ void attn_unit(const Tensors& T0, int ureq, int b, int hh, int qblk, LAS3 char* shm, const bool dummy = false) {
;     ...
;     if (near) {
;       const LAS3 float* tp = tab + (MODE ? 0 : sub * TABW) + (k0 - q0w - r32 + 4 * hi + TAB0);
; #pragma unroll
;       for (int r = 0; r < 16; ++r) { C0[r] += tp[(r & 3) + 8 * (r >> 2)]; C1[r] += tp[(r & 3) + 8 * (r >> 2) + 32]; }
;     }
;     float rm;
;     { float a = max3f(C0[0], C0[1], C1[0]), bq = max3f(C0[2], C0[3], C1[1]); a = max3f(a, C1[2], C1[3]);
; #pragma unroll
;       for (int r = 4; r < 16; r += 4) { a = max3f(a, C0[r], C0[r + 1]); bq = max3f(bq, C0[r + 2], C0[r + 3]); a = max3f(a, C1[r], C1[r + 1]); bq = max3f(bq, C1[r + 2], C1[r + 3]); }
;       a = max2f(a, bq);
;       auto rr = __builtin_amdgcn_permlane32_swap(__float_as_uint(a), __float_as_uint(a), false, false);
;       rm = max2f(__uint_as_float(rr[0]), __uint_as_float(rr[1])); }
;     if (first || __any(rm > THRL)) {
;       const float dl = first ? rm : __builtin_fmaxf(rm, 0.f);
;       mhat += dl;
; #pragma unroll
;       for (int r = 0; r < 16; ++r) { C0[r] -= dl; C1[r] -= dl; negm[r] = curcb - mhat; }
;       if (!first) {
;         const float f = __builtin_amdgcn_exp2f(-dl); l_reg *= f;
;         if (hi == 0) wsf[r32] = f;
;         asm volatile("s_waitcnt lgkmcnt(0)" ::: "memory");
; #pragma unroll
;         for (int r = 0; r < 16; ++r) { const float fr_ = wsf[crow(r, hi)];
; #pragma unroll
;           for (int d = 0; d < ND; ++d) o[d][r] *= fr_; }
.LBB0_173:
	s_mul_i32 s44, s84, 0x900
	v_or_b32_e32 v49, s85, v123
	s_lshl_b32 s19, s68, 6
	s_add_i32 s18, s44, 0
	v_sub_u32_e32 v49, s19, v49
	s_add_i32 s18, s18, 0x20800
	v_lshlrev_b32_e32 v82, 2, v124
	v_lshlrev_b32_e32 v49, 2, v49
	v_add3_u32 v49, s18, v82, v49
	v_add_u32_e32 v82, 0x480, v49
	v_add_u32_e32 v84, 0x500, v49
	v_add_u32_e32 v86, 0x488, v49
	ds_read2_b32 v[82:83], v82 offset1:1
	ds_read2_b32 v[84:85], v84 offset1:1
	ds_read2_b32 v[86:87], v86 offset1:1
	v_add_u32_e32 v88, 0x508, v49
	v_add_u32_e32 v92, 0x528, v49
	s_waitcnt lgkmcnt(2)
	v_add_f32_e32 v66, v66, v82
	v_add_f32_e32 v67, v67, v83
	s_waitcnt lgkmcnt(1)
	v_add_f32_e32 v82, v50, v84
	v_add_f32_e32 v83, v51, v85
	s_waitcnt lgkmcnt(0)
	v_add_f32_e32 v50, v68, v86
	v_add_f32_e32 v51, v69, v87
	v_add_u32_e32 v68, 0x4a0, v49
	ds_read2_b32 v[88:89], v88 offset1:1
	v_add_u32_e32 v84, 0x520, v49
	v_add_u32_e32 v85, 0x4a8, v49
	ds_read2_b32 v[68:69], v68 offset1:1
	ds_read2_b32 v[86:87], v84 offset1:1
	ds_read2_b32 v[90:91], v85 offset1:1
	ds_read2_b32 v[92:93], v92 offset1:1
	v_lshl_add_u32 v132, v123, 2, s69
	s_waitcnt lgkmcnt(3)
	v_add_f32_e32 v68, v70, v68
	v_add_f32_e32 v69, v71, v69
	s_waitcnt lgkmcnt(2)
	v_add_f32_e32 v70, v54, v86
	v_add_f32_e32 v71, v55, v87
	v_add_f32_e32 v84, v52, v88
	v_add_f32_e32 v85, v53, v89
	s_waitcnt lgkmcnt(0)
	v_add_f32_e32 v54, v56, v92
	v_add_f32_e32 v55, v57, v93
	v_add_u32_e32 v56, 0x4c0, v49
	v_add_f32_e32 v52, v72, v90
	v_add_f32_e32 v53, v73, v91
	v_add_u32_e32 v72, 0x540, v49
	v_add_u32_e32 v73, 0x4c8, v49
	ds_read2_b32 v[56:57], v56 offset1:1
	ds_read2_b32 v[86:87], v72 offset1:1
	ds_read2_b32 v[88:89], v73 offset1:1
	v_add_u32_e32 v72, 0x548, v49
	ds_read2_b32 v[90:91], v72 offset1:1
	s_waitcnt lgkmcnt(3)
	v_add_f32_e32 v72, v74, v56
	v_add_f32_e32 v73, v75, v57
	s_waitcnt lgkmcnt(2)
	v_add_f32_e32 v74, v58, v86
	v_add_f32_e32 v75, v59, v87
	v_add_u32_e32 v58, 0x4e0, v49
	s_waitcnt lgkmcnt(1)
	v_add_f32_e32 v56, v76, v88
	v_add_f32_e32 v57, v77, v89
	v_add_u32_e32 v76, 0x560, v49
	v_add_u32_e32 v77, 0x4e8, v49
	v_add_u32_e32 v49, 0x568, v49
	ds_read2_b32 v[58:59], v58 offset1:1
	ds_read2_b32 v[88:89], v76 offset1:1
	ds_read2_b32 v[92:93], v77 offset1:1
	ds_read2_b32 v[94:95], v49 offset1:1
	v_max3_f32 v49, v66, v67, v82
	s_waitcnt lgkmcnt(4)
	v_add_f32_e32 v86, v60, v90
	v_add_f32_e32 v87, v61, v91
	v_max3_f32 v49, v49, v84, v85
	s_waitcnt lgkmcnt(3)
	v_add_f32_e32 v76, v78, v58
	v_add_f32_e32 v77, v79, v59
	s_waitcnt lgkmcnt(0)
	v_add_f32_e32 v60, v64, v94
	v_add_f32_e32 v61, v65, v95
	v_max3_f32 v64, v50, v51, v83
	v_max3_f32 v49, v49, v68, v69
	v_add_f32_e32 v58, v80, v92
	v_add_f32_e32 v59, v81, v93
	v_max3_f32 v64, v64, v52, v53
	v_max3_f32 v49, v49, v70, v71
	v_add_f32_e32 v62, v62, v88
	v_add_f32_e32 v63, v63, v89
	v_max3_f32 v64, v64, v54, v55
	v_max3_f32 v49, v49, v72, v73
	s_nop 0
	v_max3_f32 v64, v64, v56, v57
	v_max3_f32 v49, v49, v74, v75
	s_nop 0
	v_max3_f32 v64, v64, v86, v87
	v_max3_f32 v49, v49, v76, v77
	s_nop 0
	v_max3_f32 v64, v64, v58, v59
	v_max3_f32 v49, v49, v62, v63
	s_nop 0
	v_max3_f32 v64, v64, v60, v61
	s_nop 0
	v_max_f32_e32 v49, v49, v64
	s_nop 0
	v_mov_b32_e32 v64, v49
	s_nop 1
	v_permlane32_swap_b32_e32 v49, v64
	v_max_f32_e32 v49, v49, v64
	s_nop 0
	v_cmp_lt_f32_e32 vcc, s78, v49
	s_cbranch_vccz .LBB0_177
	v_max_f32_e32 v48, v49, v49
	v_max_f32_e32 v49, 0, v48
	v_exp_f32_e64 v64, -v49
	s_and_saveexec_b64 s[40:41], s[4:5]
	ds_write_b32 v132, v64
	s_or_b64 exec, exec, s[40:41]
	s_waitcnt lgkmcnt(0)
	v_lshl_add_u32 v65, v124, 2, s69
	ds_read_b128 v[78:81], v65 offset:64
	ds_read_b128 v[88:91], v65 offset:96
	ds_read_b128 v[92:95], v65
	ds_read_b128 v[108:111], v65 offset:32
	v_add_f32_e32 v131, v131, v49
	v_sub_f32_e32 v48, 0, v131
	v_sub_f32_e32 v66, v66, v49
	v_sub_f32_e32 v67, v67, v49
	v_sub_f32_e32 v50, v50, v49
	v_sub_f32_e32 v51, v51, v49
	v_sub_f32_e32 v68, v68, v49
	v_sub_f32_e32 v69, v69, v49
	v_sub_f32_e32 v52, v52, v49
	v_sub_f32_e32 v53, v53, v49
	v_sub_f32_e32 v72, v72, v49
	v_sub_f32_e32 v73, v73, v49
	v_sub_f32_e32 v56, v56, v49
	v_sub_f32_e32 v57, v57, v49
	v_sub_f32_e32 v76, v76, v49
	v_sub_f32_e32 v77, v77, v49
	v_sub_f32_e32 v58, v58, v49
	v_sub_f32_e32 v59, v59, v49
	v_sub_f32_e32 v82, v82, v49
	v_sub_f32_e32 v83, v83, v49
	v_sub_f32_e32 v84, v84, v49
	v_sub_f32_e32 v85, v85, v49
	v_sub_f32_e32 v70, v70, v49
	v_sub_f32_e32 v71, v71, v49
	v_sub_f32_e32 v54, v54, v49
	v_sub_f32_e32 v55, v55, v49
	v_sub_f32_e32 v74, v74, v49
	v_sub_f32_e32 v75, v75, v49
	v_sub_f32_e32 v86, v86, v49
	v_sub_f32_e32 v87, v87, v49
	v_sub_f32_e32 v62, v62, v49
	v_sub_f32_e32 v63, v63, v49
	v_sub_f32_e32 v60, v60, v49
	v_sub_f32_e32 v61, v61, v49
	v_mul_f32_e32 v125, v125, v64
	s_waitcnt lgkmcnt(2)
	v_pk_mul_f32 v[46:47], v[46:47], v[90:91]
	v_pk_mul_f32 v[42:43], v[42:43], v[80:81]
	s_waitcnt lgkmcnt(0)
	v_pk_mul_f32 v[38:39], v[38:39], v[110:111]
	v_pk_mul_f32 v[34:35], v[34:35], v[94:95]
	v_pk_mul_f32 v[44:45], v[44:45], v[88:89]
	v_pk_mul_f32 v[40:41], v[40:41], v[78:79]
	v_pk_mul_f32 v[36:37], v[36:37], v[108:109]
	v_pk_mul_f32 v[32:33], v[32:33], v[92:93]
	v_pk_mul_f32 v[30:31], v[30:31], v[90:91]
	v_pk_mul_f32 v[26:27], v[26:27], v[80:81]
	v_pk_mul_f32 v[22:23], v[22:23], v[110:111]
	v_pk_mul_f32 v[18:19], v[18:19], v[94:95]
	v_pk_mul_f32 v[28:29], v[28:29], v[88:89]
	v_pk_mul_f32 v[24:25], v[24:25], v[78:79]
	v_pk_mul_f32 v[20:21], v[20:21], v[108:109]
	v_pk_mul_f32 v[16:17], v[16:17], v[92:93]

; #define LAS3 __attribute__((address_space(3)))
; __device__ __forceinline__ int crow(int r, int hi) { return (r & 3) + 8 * (r >> 2) + 4 * hi; }
; __device__ __forceinline__ float max2f(float a, float b) { float r; asm("v_max_f32_e32 %0, %1, %2" : "=v"(r) : "v"(a), "v"(b)); return r; }
; __device__ __forceinline__ float max3f(float a, float b, float c) { float r; asm("v_max3_f32 %0, %1, %2, %3" : "=v"(r) : "v"(a), "v"(b), "v"(c)); return r; }
; template <int MODE>
; __device__ __forceinline__ void attn_unit(const Tensors& T0, int ureq, int b, int hh, int qblk, LAS3 char* shm, const bool dummy = false) {
;     ...
;     if (near) {
;       const LAS3 float* tp = tab + (MODE ? 0 : sub * TABW) + (k0 - q0w - r32 + 4 * hi + TAB0);
; #pragma unroll
;       for (int r = 0; r < 16; ++r) { C0[r] += tp[(r & 3) + 8 * (r >> 2)]; C1[r] += tp[(r & 3) + 8 * (r >> 2) + 32]; }
;     }
;     float rm;
;     { float a = max3f(C0[0], C0[1], C1[0]), bq = max3f(C0[2], C0[3], C1[1]); a = max3f(a, C1[2], C1[3]);
; #pragma unroll
;       for (int r = 4; r < 16; r += 4) { a = max3f(a, C0[r], C0[r + 1]); bq = max3f(bq, C0[r + 2], C0[r + 3]); a = max3f(a, C1[r], C1[r + 1]); bq = max3f(bq, C1[r + 2], C1[r + 3]); }
;       a = max2f(a, bq);
;       auto rr = __builtin_amdgcn_permlane32_swap(__float_as_uint(a), __float_as_uint(a), false, false);
;       rm = max2f(__uint_as_float(rr[0]), __uint_as_float(rr[1])); }
;     if (first || __any(rm > THRL)) {
;       const float dl = first ? rm : __builtin_fmaxf(rm, 0.f);
;       mhat += dl;
; #pragma unroll
;       for (int r = 0; r < 16; ++r) { C0[r] -= dl; C1[r] -= dl; negm[r] = curcb - mhat; }
;       if (!first) {
;         const float f = __builtin_amdgcn_exp2f(-dl); l_reg *= f;
;         if (hi == 0) wsf[r32] = f;
;         asm volatile("s_waitcnt lgkmcnt(0)" ::: "memory");
; #pragma unroll
;         for (int r = 0; r < 16; ++r) { const float fr_ = wsf[crow(r, hi)];
; #pragma unroll
;           for (int d = 0; d < ND; ++d) o[d][r] *= fr_; }
.LBB0_205:
	ds_read2_b32 v[108:109], v134 offset1:1
	ds_read2_b32 v[110:111], v134 offset0:32 offset1:33
	ds_read2_b32 v[114:115], v134 offset0:2 offset1:3
	ds_read2_b32 v[118:119], v134 offset0:8 offset1:9
	ds_read2_b32 v[136:137], v134 offset0:10 offset1:11
	s_waitcnt lgkmcnt(4)
	v_add_f32_e32 v112, v80, v108
	v_add_f32_e32 v113, v81, v109
	ds_read2_b32 v[80:81], v134 offset0:34 offset1:35
	ds_read2_b32 v[138:139], v134 offset0:40 offset1:41
	ds_read2_b32 v[140:141], v134 offset0:42 offset1:43
	s_waitcnt lgkmcnt(6)
	v_add_f32_e32 v116, v64, v110
	v_add_f32_e32 v117, v65, v111
	s_waitcnt lgkmcnt(5)
	v_add_f32_e32 v108, v82, v114
	v_add_f32_e32 v109, v83, v115
	s_waitcnt lgkmcnt(2)
	v_add_f32_e32 v110, v66, v80
	v_add_f32_e32 v111, v67, v81
	v_add_f32_e32 v80, v84, v118
	v_add_f32_e32 v81, v85, v119
	s_waitcnt lgkmcnt(1)
	v_add_f32_e32 v82, v68, v138
	v_add_f32_e32 v83, v69, v139
	v_add_f32_e32 v68, v86, v136
	v_add_f32_e32 v69, v87, v137
	ds_read2_b32 v[64:65], v134 offset0:16 offset1:17
	ds_read2_b32 v[66:67], v134 offset0:48 offset1:49
	ds_read2_b32 v[84:85], v134 offset0:18 offset1:19
	ds_read2_b32 v[118:119], v134 offset0:24 offset1:25
	ds_read2_b32 v[136:137], v134 offset0:26 offset1:27
	s_waitcnt lgkmcnt(5)
	v_add_f32_e32 v70, v70, v140
	v_add_f32_e32 v71, v71, v141
	s_waitcnt lgkmcnt(4)
	v_add_f32_e32 v88, v88, v64
	v_add_f32_e32 v89, v89, v65
	ds_read2_b32 v[64:65], v134 offset0:50 offset1:51
	ds_read2_b32 v[138:139], v134 offset0:56 offset1:57
	ds_read2_b32 v[140:141], v134 offset0:58 offset1:59
	s_waitcnt lgkmcnt(5)
	v_add_f32_e32 v84, v90, v84
	v_add_f32_e32 v85, v91, v85
	v_add_f32_e32 v114, v72, v66
	v_add_f32_e32 v115, v73, v67
	s_waitcnt lgkmcnt(2)
	v_add_f32_e32 v86, v74, v64
	v_add_f32_e32 v87, v75, v65
	s_waitcnt lgkmcnt(1)
	v_add_f32_e32 v74, v76, v138
	v_add_f32_e32 v75, v77, v139
	v_max3_f32 v76, v112, v113, v116
	v_max3_f32 v77, v108, v109, v117
	v_add_f32_e32 v72, v92, v118
	v_add_f32_e32 v73, v93, v119
	v_max3_f32 v76, v76, v110, v111
	v_max3_f32 v77, v77, v68, v69
	v_add_f32_e32 v64, v94, v136
	v_add_f32_e32 v65, v95, v137
	v_max3_f32 v76, v76, v80, v81
	v_max3_f32 v77, v77, v70, v71
	s_waitcnt lgkmcnt(0)
	v_add_f32_e32 v66, v78, v140
	v_add_f32_e32 v67, v79, v141
	v_max3_f32 v76, v76, v82, v83
	v_max3_f32 v77, v77, v84, v85
	s_nop 0
	v_max3_f32 v76, v76, v88, v89
	v_max3_f32 v77, v77, v86, v87
	s_nop 0
	v_max3_f32 v76, v76, v114, v115
	v_max3_f32 v77, v77, v64, v65
	s_nop 0
	v_max3_f32 v76, v76, v72, v73
	v_max3_f32 v77, v77, v66, v67
	s_nop 0
	v_max3_f32 v76, v76, v74, v75
	s_nop 0
	v_max_f32_e32 v76, v76, v77
	s_nop 0
	v_mov_b32_e32 v77, v76
	s_nop 1
	v_permlane32_swap_b32_e32 v76, v77
	v_max_f32_e32 v76, v76, v77
	s_nop 0
	v_cmp_lt_f32_e32 vcc, s78, v76
	s_cbranch_vccz .LBB0_209
	v_max_f32_e32 v48, v76, v76
	v_max_f32_e32 v48, 0, v48
	v_exp_f32_e64 v49, -v48
	s_and_saveexec_b64 s[38:39], s[4:5]
	ds_write_b32 v132, v49
	s_or_b64 exec, exec, s[38:39]
	s_waitcnt lgkmcnt(0)
	ds_read_b128 v[50:53], v133 offset:64
	ds_read_b128 v[54:57], v133 offset:96
	ds_read_b128 v[58:61], v133
	ds_read_b128 v[76:79], v133 offset:32
	v_add_f32_e32 v131, v131, v48
	v_sub_f32_e32 v63, 0, v131
	v_sub_f32_e32 v112, v112, v48
	v_sub_f32_e32 v113, v113, v48
	v_sub_f32_e32 v108, v108, v48
	v_sub_f32_e32 v109, v109, v48
	v_sub_f32_e32 v80, v80, v48
	v_sub_f32_e32 v81, v81, v48
	v_sub_f32_e32 v68, v68, v48
	v_sub_f32_e32 v69, v69, v48
	v_sub_f32_e32 v88, v88, v48
	v_sub_f32_e32 v89, v89, v48
	v_sub_f32_e32 v84, v84, v48
	v_sub_f32_e32 v85, v85, v48
	v_sub_f32_e32 v72, v72, v48
	v_sub_f32_e32 v73, v73, v48
	v_sub_f32_e32 v64, v64, v48
	v_sub_f32_e32 v65, v65, v48
	v_sub_f32_e32 v116, v116, v48
	v_sub_f32_e32 v117, v117, v48
	v_sub_f32_e32 v110, v110, v48
	v_sub_f32_e32 v111, v111, v48
	v_sub_f32_e32 v82, v82, v48
	v_sub_f32_e32 v83, v83, v48
	v_sub_f32_e32 v70, v70, v48
	v_sub_f32_e32 v71, v71, v48
	v_sub_f32_e32 v114, v114, v48
	v_sub_f32_e32 v115, v115, v48
	v_sub_f32_e32 v86, v86, v48
	v_sub_f32_e32 v87, v87, v48
	v_sub_f32_e32 v74, v74, v48
	v_sub_f32_e32 v75, v75, v48
	v_sub_f32_e32 v66, v66, v48
	v_sub_f32_e32 v67, v67, v48
	v_mul_f32_e32 v125, v125, v49
	s_waitcnt lgkmcnt(2)
	v_pk_mul_f32 v[46:47], v[46:47], v[56:57]
	v_pk_mul_f32 v[42:43], v[42:43], v[52:53]
	s_waitcnt lgkmcnt(0)
	v_pk_mul_f32 v[38:39], v[38:39], v[78:79]
	v_pk_mul_f32 v[34:35], v[34:35], v[60:61]
	v_pk_mul_f32 v[44:45], v[44:45], v[54:55]
	v_pk_mul_f32 v[40:41], v[40:41], v[50:51]
	v_pk_mul_f32 v[36:37], v[36:37], v[76:77]
	v_pk_mul_f32 v[32:33], v[32:33], v[58:59]
	v_pk_mul_f32 v[30:31], v[30:31], v[56:57]
	v_pk_mul_f32 v[26:27], v[26:27], v[52:53]
	v_pk_mul_f32 v[22:23], v[22:23], v[78:79]
	v_pk_mul_f32 v[18:19], v[18:19], v[60:61]
	v_pk_mul_f32 v[28:29], v[28:29], v[54:55]
	v_pk_mul_f32 v[24:25], v[24:25], v[50:51]
	v_pk_mul_f32 v[20:21], v[20:21], v[76:77]
	v_pk_mul_f32 v[16:17], v[16:17], v[58:59]
	v_mov_b32_e32 v62, v63
	v_mov_b32_e32 v61, v63
	v_mov_b32_e32 v60, v63
	v_mov_b32_e32 v59, v63
	v_mov_b32_e32 v58, v63
	v_mov_b32_e32 v57, v63
	v_mov_b32_e32 v56, v63
	v_mov_b32_e32 v55, v63
	v_mov_b32_e32 v54, v63
	v_mov_b32_e32 v53, v63
	v_mov_b32_e32 v52, v63
	v_mov_b32_e32 v51, v63
	v_mov_b32_e32 v50, v63
	v_mov_b32_e32 v49, v63
	v_mov_b32_e32 v48, v63
